# grid barrier: non-last blocks poll the top generation word directly instead of the per-XCD relay word
# speedup vs baseline: 1.0005x; 1.0005x over previous
; __device__ __forceinline__ unsigned xb_ld(unsigned* p)              { return __hip_atomic_load(p, __ATOMIC_RELAXED, __HIP_MEMORY_SCOPE_AGENT); }
; __device__ __forceinline__ unsigned xb_add(unsigned* p, unsigned v) { return __hip_atomic_fetch_add(p, v, __ATOMIC_RELAXED, __HIP_MEMORY_SCOPE_AGENT); }
; #define XB_SPIN(cond, bar) do { unsigned _sp = 0; while (cond) { __builtin_amdgcn_s_sleep(1); \
;     if ((++_sp & 255u) == 0u) { if (xb_ld(&(bar)[XB_TMO])) break; if (_sp > XB_SPIN_CAP) { atomicAdd(&(bar)[XB_TMO], 1u); break; } } } } while (0)
; __device__ __forceinline__ void xcd_barrier(const XcdBarrier& b, bool lead) {
;     ...
;         const unsigned old = xb_add(&bar[XB_XSUB(b.x)], 1u);
;         const unsigned gen = old / nloc;
;         if (old + 1u == (gen + 1u) * nloc) {
;             __builtin_amdgcn_fence(__ATOMIC_RELEASE, "agent");
;             asm volatile("s_waitcnt vmcnt(0)" ::: "memory");
;             const unsigned og = xb_add(&bar[XB_TOP], 1u);
;             const unsigned tg = og / nx;
;             if (og + 1u == (tg + 1u) * nx) xb_add(&bar[XB_TOPGEN], 1u);
;             else XB_SPIN(xb_ld(&bar[XB_TOPGEN]) == tg, bar);
;             __builtin_amdgcn_fence(__ATOMIC_ACQUIRE, "agent");
;             xb_add(&bar[XB_XGEN(b.x)], 1u);
;             asm volatile("s_waitcnt vmcnt(0)" ::: "memory");
;         } else {
;             XB_SPIN(xb_ld(&bar[XB_XGEN(b.x)]) == gen, bar);
.LBB0_240:
	s_or_b64 exec, exec, s[16:17]
	v_cvt_f32_u32_e32 v4, v2
	s_waitcnt vmcnt(0)
	v_readfirstlane_b32 s7, v3
	v_sub_u32_e32 v3, 0, v2
	v_rcp_iflag_f32_e32 v4, v4
	v_add_u32_e32 v5, s7, v1
	v_mul_f32_e32 v4, 0x4f7ffffe, v4
	v_cvt_u32_f32_e32 v4, v4
	v_mul_lo_u32 v1, v3, v4
	v_mul_hi_u32 v1, v4, v1
	v_add_u32_e32 v1, v4, v1
	v_mul_hi_u32 v1, v5, v1
	v_mul_lo_u32 v3, v1, v2
	v_sub_u32_e32 v3, v5, v3
	v_add_u32_e32 v4, 1, v1
	v_cmp_ge_u32_e32 vcc, v3, v2
	s_nop 1
	v_cndmask_b32_e32 v1, v1, v4, vcc
	v_sub_u32_e32 v4, v3, v2
	v_cndmask_b32_e32 v3, v3, v4, vcc
	v_add_u32_e32 v4, 1, v1
	v_cmp_ge_u32_e32 vcc, v3, v2
	v_add_u32_e32 v3, 1, v5
	s_nop 0
	v_cndmask_b32_e32 v1, v1, v4, vcc
	v_mul_lo_u32 v4, v2, v1
	v_add_u32_e32 v2, v4, v2
	v_cmp_ne_u32_e32 vcc, v3, v2
	s_and_saveexec_b64 s[12:13], vcc
	s_xor_b64 s[12:13], exec, s[12:13]
	s_cbranch_execz .LBB0_254
	s_waitcnt lgkmcnt(0)
	v_mov_b32_e32 v0, 0x3100
	global_load_dword v0, v0, s[56:57] offset:1024 sc1
	s_add_u32 s18, s56, 0x3500
	s_addc_u32 s19, s57, 0
	s_waitcnt vmcnt(0)
	v_cmp_eq_u32_e32 vcc, v0, v1
	s_and_saveexec_b64 s[16:17], vcc
	s_cbranch_execz .LBB0_253
	s_mov_b32 s7, 1
	s_mov_b64 s[24:25], 0
	v_mov_b32_e32 v0, 0
	s_branch .LBB0_244

; __device__ __forceinline__ unsigned xb_ld(unsigned* p)              { return __hip_atomic_load(p, __ATOMIC_RELAXED, __HIP_MEMORY_SCOPE_AGENT); }
; __device__ __forceinline__ unsigned xb_add(unsigned* p, unsigned v) { return __hip_atomic_fetch_add(p, v, __ATOMIC_RELAXED, __HIP_MEMORY_SCOPE_AGENT); }
; #define XB_SPIN(cond, bar) do { unsigned _sp = 0; while (cond) { __builtin_amdgcn_s_sleep(1); \
;     if ((++_sp & 255u) == 0u) { if (xb_ld(&(bar)[XB_TMO])) break; if (_sp > XB_SPIN_CAP) { atomicAdd(&(bar)[XB_TMO], 1u); break; } } } } while (0)
; __device__ __forceinline__ void xcd_barrier(const XcdBarrier& b, bool lead) {
;     ...
;         const unsigned old = xb_add(&bar[XB_XSUB(b.x)], 1u);
;         const unsigned gen = old / nloc;
;         if (old + 1u == (gen + 1u) * nloc) {
;             __builtin_amdgcn_fence(__ATOMIC_RELEASE, "agent");
;             asm volatile("s_waitcnt vmcnt(0)" ::: "memory");
;             const unsigned og = xb_add(&bar[XB_TOP], 1u);
;             const unsigned tg = og / nx;
;             if (og + 1u == (tg + 1u) * nx) xb_add(&bar[XB_TOPGEN], 1u);
;             else XB_SPIN(xb_ld(&bar[XB_TOPGEN]) == tg, bar);
;             __builtin_amdgcn_fence(__ATOMIC_ACQUIRE, "agent");
;             xb_add(&bar[XB_XGEN(b.x)], 1u);
;             asm volatile("s_waitcnt vmcnt(0)" ::: "memory");
;         } else {
;             XB_SPIN(xb_ld(&bar[XB_XGEN(b.x)]) == gen, bar);
.LBB0_334:
	s_or_b64 exec, exec, s[10:11]
	v_cvt_f32_u32_e32 v4, v2
	s_waitcnt vmcnt(0)
	v_readfirstlane_b32 s8, v3
	v_sub_u32_e32 v3, 0, v2
	v_rcp_iflag_f32_e32 v4, v4
	v_add_u32_e32 v5, s8, v1
	v_mul_f32_e32 v4, 0x4f7ffffe, v4
	v_cvt_u32_f32_e32 v4, v4
	v_mul_lo_u32 v1, v3, v4
	v_mul_hi_u32 v1, v4, v1
	v_add_u32_e32 v1, v4, v1
	v_mul_hi_u32 v1, v5, v1
	v_mul_lo_u32 v3, v1, v2
	v_sub_u32_e32 v3, v5, v3
	v_add_u32_e32 v4, 1, v1
	v_cmp_ge_u32_e32 vcc, v3, v2
	s_nop 1
	v_cndmask_b32_e32 v1, v1, v4, vcc
	v_sub_u32_e32 v4, v3, v2
	v_cndmask_b32_e32 v3, v3, v4, vcc
	v_add_u32_e32 v4, 1, v1
	v_cmp_ge_u32_e32 vcc, v3, v2
	v_add_u32_e32 v3, 1, v5
	s_nop 0
	v_cndmask_b32_e32 v1, v1, v4, vcc
	v_mul_lo_u32 v4, v2, v1
	v_add_u32_e32 v2, v4, v2
	v_cmp_ne_u32_e32 vcc, v3, v2
	s_and_saveexec_b64 s[8:9], vcc
	s_xor_b64 s[8:9], exec, s[8:9]
	s_cbranch_execz .LBB0_348
	s_waitcnt lgkmcnt(0)
	v_mov_b32_e32 v0, 0x3100
	global_load_dword v0, v0, s[56:57] offset:1024 sc1
	s_add_u32 s12, s56, 0x3500
	s_addc_u32 s13, s57, 0
	s_waitcnt vmcnt(0)
	v_cmp_eq_u32_e32 vcc, v0, v1
	s_and_saveexec_b64 s[10:11], vcc
	s_cbranch_execz .LBB0_347
	s_mov_b32 s36, 1
	s_mov_b64 s[16:17], 0
	v_mov_b32_e32 v0, 0
	s_branch .LBB0_338

; __device__ __forceinline__ unsigned xb_ld(unsigned* p)              { return __hip_atomic_load(p, __ATOMIC_RELAXED, __HIP_MEMORY_SCOPE_AGENT); }
; __device__ __forceinline__ unsigned xb_add(unsigned* p, unsigned v) { return __hip_atomic_fetch_add(p, v, __ATOMIC_RELAXED, __HIP_MEMORY_SCOPE_AGENT); }
; #define XB_SPIN(cond, bar) do { unsigned _sp = 0; while (cond) { __builtin_amdgcn_s_sleep(1); \
;     if ((++_sp & 255u) == 0u) { if (xb_ld(&(bar)[XB_TMO])) break; if (_sp > XB_SPIN_CAP) { atomicAdd(&(bar)[XB_TMO], 1u); break; } } } } while (0)
; __device__ __forceinline__ void xcd_barrier(const XcdBarrier& b, bool lead) {
;     ...
;         const unsigned old = xb_add(&bar[XB_XSUB(b.x)], 1u);
;         const unsigned gen = old / nloc;
;         if (old + 1u == (gen + 1u) * nloc) {
;             __builtin_amdgcn_fence(__ATOMIC_RELEASE, "agent");
;             asm volatile("s_waitcnt vmcnt(0)" ::: "memory");
;             const unsigned og = xb_add(&bar[XB_TOP], 1u);
;             const unsigned tg = og / nx;
;             if (og + 1u == (tg + 1u) * nx) xb_add(&bar[XB_TOPGEN], 1u);
;             else XB_SPIN(xb_ld(&bar[XB_TOPGEN]) == tg, bar);
;             __builtin_amdgcn_fence(__ATOMIC_ACQUIRE, "agent");
;             xb_add(&bar[XB_XGEN(b.x)], 1u);
;             asm volatile("s_waitcnt vmcnt(0)" ::: "memory");
;         } else {
;             XB_SPIN(xb_ld(&bar[XB_XGEN(b.x)]) == gen, bar);
.LBB0_734:
	s_or_b64 exec, exec, s[10:11]
	v_cvt_f32_u32_e32 v4, v2
	s_waitcnt vmcnt(0)
	v_readfirstlane_b32 s8, v3
	v_sub_u32_e32 v3, 0, v2
	v_rcp_iflag_f32_e32 v4, v4
	v_add_u32_e32 v5, s8, v1
	v_mul_f32_e32 v4, 0x4f7ffffe, v4
	v_cvt_u32_f32_e32 v4, v4
	v_mul_lo_u32 v1, v3, v4
	v_mul_hi_u32 v1, v4, v1
	v_add_u32_e32 v1, v4, v1
	v_mul_hi_u32 v1, v5, v1
	v_mul_lo_u32 v3, v1, v2
	v_sub_u32_e32 v3, v5, v3
	v_add_u32_e32 v4, 1, v1
	v_cmp_ge_u32_e32 vcc, v3, v2
	s_nop 1
	v_cndmask_b32_e32 v1, v1, v4, vcc
	v_sub_u32_e32 v4, v3, v2
	v_cndmask_b32_e32 v3, v3, v4, vcc
	v_add_u32_e32 v4, 1, v1
	v_cmp_ge_u32_e32 vcc, v3, v2
	v_add_u32_e32 v3, 1, v5
	s_nop 0
	v_cndmask_b32_e32 v1, v1, v4, vcc
	v_mul_lo_u32 v4, v2, v1
	v_add_u32_e32 v2, v4, v2
	v_cmp_ne_u32_e32 vcc, v3, v2
	s_and_saveexec_b64 s[8:9], vcc
	s_xor_b64 s[8:9], exec, s[8:9]
	s_cbranch_execz .LBB0_748
	s_waitcnt lgkmcnt(0)
	v_mov_b32_e32 v0, 0x3100
	global_load_dword v0, v0, s[56:57] offset:1024 sc1
	s_add_u32 s12, s56, 0x3500
	s_addc_u32 s13, s57, 0
	s_waitcnt vmcnt(0)
	v_cmp_eq_u32_e32 vcc, v0, v1
	s_and_saveexec_b64 s[10:11], vcc
	s_cbranch_execz .LBB0_747
	s_mov_b32 s38, 1
	s_mov_b64 s[16:17], 0
	v_mov_b32_e32 v0, 0
	s_branch .LBB0_738

; __device__ __forceinline__ unsigned xb_ld(unsigned* p)              { return __hip_atomic_load(p, __ATOMIC_RELAXED, __HIP_MEMORY_SCOPE_AGENT); }
; __device__ __forceinline__ unsigned xb_add(unsigned* p, unsigned v) { return __hip_atomic_fetch_add(p, v, __ATOMIC_RELAXED, __HIP_MEMORY_SCOPE_AGENT); }
; #define XB_SPIN(cond, bar) do { unsigned _sp = 0; while (cond) { __builtin_amdgcn_s_sleep(1); \
;     if ((++_sp & 255u) == 0u) { if (xb_ld(&(bar)[XB_TMO])) break; if (_sp > XB_SPIN_CAP) { atomicAdd(&(bar)[XB_TMO], 1u); break; } } } } while (0)
; __device__ __forceinline__ void xcd_barrier(const XcdBarrier& b, bool lead) {
;     ...
;         const unsigned old = xb_add(&bar[XB_XSUB(b.x)], 1u);
;         const unsigned gen = old / nloc;
;         if (old + 1u == (gen + 1u) * nloc) {
;             __builtin_amdgcn_fence(__ATOMIC_RELEASE, "agent");
;             asm volatile("s_waitcnt vmcnt(0)" ::: "memory");
;             const unsigned og = xb_add(&bar[XB_TOP], 1u);
;             const unsigned tg = og / nx;
;             if (og + 1u == (tg + 1u) * nx) xb_add(&bar[XB_TOPGEN], 1u);
;             else XB_SPIN(xb_ld(&bar[XB_TOPGEN]) == tg, bar);
;             __builtin_amdgcn_fence(__ATOMIC_ACQUIRE, "agent");
;             xb_add(&bar[XB_XGEN(b.x)], 1u);
;             asm volatile("s_waitcnt vmcnt(0)" ::: "memory");
;         } else {
;             XB_SPIN(xb_ld(&bar[XB_XGEN(b.x)]) == gen, bar);
.LBB0_1008:
	s_or_b64 exec, exec, s[10:11]
	v_cvt_f32_u32_e32 v4, v2
	s_waitcnt vmcnt(0)
	v_readfirstlane_b32 s8, v3
	v_sub_u32_e32 v3, 0, v2
	v_rcp_iflag_f32_e32 v4, v4
	v_add_u32_e32 v5, s8, v1
	v_mul_f32_e32 v4, 0x4f7ffffe, v4
	v_cvt_u32_f32_e32 v4, v4
	v_mul_lo_u32 v1, v3, v4
	v_mul_hi_u32 v1, v4, v1
	v_add_u32_e32 v1, v4, v1
	v_mul_hi_u32 v1, v5, v1
	v_mul_lo_u32 v3, v1, v2
	v_sub_u32_e32 v3, v5, v3
	v_add_u32_e32 v4, 1, v1
	v_cmp_ge_u32_e32 vcc, v3, v2
	s_nop 1
	v_cndmask_b32_e32 v1, v1, v4, vcc
	v_sub_u32_e32 v4, v3, v2
	v_cndmask_b32_e32 v3, v3, v4, vcc
	v_add_u32_e32 v4, 1, v1
	v_cmp_ge_u32_e32 vcc, v3, v2
	v_add_u32_e32 v3, 1, v5
	s_nop 0
	v_cndmask_b32_e32 v1, v1, v4, vcc
	v_mul_lo_u32 v4, v2, v1
	v_add_u32_e32 v2, v4, v2
	v_cmp_ne_u32_e32 vcc, v3, v2
	s_and_saveexec_b64 s[8:9], vcc
	s_xor_b64 s[8:9], exec, s[8:9]
	s_cbranch_execz .LBB0_1022
	s_waitcnt lgkmcnt(0)
	v_mov_b32_e32 v0, 0x3100
	global_load_dword v0, v0, s[56:57] offset:1024 sc1
	s_add_u32 s12, s56, 0x3500
	s_addc_u32 s13, s57, 0
	s_waitcnt vmcnt(0)
	v_cmp_eq_u32_e32 vcc, v0, v1
	s_and_saveexec_b64 s[10:11], vcc
	s_cbranch_execz .LBB0_1021
	s_mov_b32 s34, 1
	s_mov_b64 s[16:17], 0
	v_mov_b32_e32 v0, 0
	s_branch .LBB0_1012

; __device__ __forceinline__ unsigned xb_ld(unsigned* p)              { return __hip_atomic_load(p, __ATOMIC_RELAXED, __HIP_MEMORY_SCOPE_AGENT); }
; __device__ __forceinline__ unsigned xb_add(unsigned* p, unsigned v) { return __hip_atomic_fetch_add(p, v, __ATOMIC_RELAXED, __HIP_MEMORY_SCOPE_AGENT); }
; #define XB_SPIN(cond, bar) do { unsigned _sp = 0; while (cond) { __builtin_amdgcn_s_sleep(1); \
;     if ((++_sp & 255u) == 0u) { if (xb_ld(&(bar)[XB_TMO])) break; if (_sp > XB_SPIN_CAP) { atomicAdd(&(bar)[XB_TMO], 1u); break; } } } } while (0)
; __device__ __forceinline__ void xcd_barrier(const XcdBarrier& b, bool lead) {
;     ...
;         const unsigned old = xb_add(&bar[XB_XSUB(b.x)], 1u);
;         const unsigned gen = old / nloc;
;         if (old + 1u == (gen + 1u) * nloc) {
;             __builtin_amdgcn_fence(__ATOMIC_RELEASE, "agent");
;             asm volatile("s_waitcnt vmcnt(0)" ::: "memory");
;             const unsigned og = xb_add(&bar[XB_TOP], 1u);
;             const unsigned tg = og / nx;
;             if (og + 1u == (tg + 1u) * nx) xb_add(&bar[XB_TOPGEN], 1u);
;             else XB_SPIN(xb_ld(&bar[XB_TOPGEN]) == tg, bar);
;             __builtin_amdgcn_fence(__ATOMIC_ACQUIRE, "agent");
;             xb_add(&bar[XB_XGEN(b.x)], 1u);
;             asm volatile("s_waitcnt vmcnt(0)" ::: "memory");
;         } else {
;             XB_SPIN(xb_ld(&bar[XB_XGEN(b.x)]) == gen, bar);
.LBB0_1666:
	s_or_b64 exec, exec, s[16:17]
	v_cvt_f32_u32_e32 v4, v2
	s_waitcnt vmcnt(0)
	v_readfirstlane_b32 s12, v3
	v_sub_u32_e32 v3, 0, v2
	v_rcp_iflag_f32_e32 v4, v4
	v_add_u32_e32 v5, s12, v1
	v_mul_f32_e32 v4, 0x4f7ffffe, v4
	v_cvt_u32_f32_e32 v4, v4
	v_mul_lo_u32 v1, v3, v4
	v_mul_hi_u32 v1, v4, v1
	v_add_u32_e32 v1, v4, v1
	v_mul_hi_u32 v1, v5, v1
	v_mul_lo_u32 v3, v1, v2
	v_sub_u32_e32 v3, v5, v3
	v_add_u32_e32 v4, 1, v1
	v_cmp_ge_u32_e32 vcc, v3, v2
	s_nop 1
	v_cndmask_b32_e32 v1, v1, v4, vcc
	v_sub_u32_e32 v4, v3, v2
	v_cndmask_b32_e32 v3, v3, v4, vcc
	v_add_u32_e32 v4, 1, v1
	v_cmp_ge_u32_e32 vcc, v3, v2
	v_add_u32_e32 v3, 1, v5
	s_nop 0
	v_cndmask_b32_e32 v1, v1, v4, vcc
	v_mul_lo_u32 v4, v2, v1
	v_add_u32_e32 v2, v4, v2
	v_cmp_ne_u32_e32 vcc, v3, v2
	s_and_saveexec_b64 s[12:13], vcc
	s_xor_b64 s[12:13], exec, s[12:13]
	s_cbranch_execz .LBB0_1680
	s_waitcnt lgkmcnt(0)
	v_mov_b32_e32 v0, 0x3100
	global_load_dword v0, v0, s[56:57] offset:1024 sc1
	s_add_u32 s18, s56, 0x3500
	s_addc_u32 s19, s57, 0
	s_waitcnt vmcnt(0)
	v_cmp_eq_u32_e32 vcc, v0, v1
	s_and_saveexec_b64 s[16:17], vcc
	s_cbranch_execz .LBB0_1679
	s_mov_b32 s34, 1
	s_mov_b64 s[20:21], 0
	v_mov_b32_e32 v0, 0
	s_branch .LBB0_1670

; __device__ __forceinline__ unsigned xb_ld(unsigned* p)              { return __hip_atomic_load(p, __ATOMIC_RELAXED, __HIP_MEMORY_SCOPE_AGENT); }
; __device__ __forceinline__ unsigned xb_add(unsigned* p, unsigned v) { return __hip_atomic_fetch_add(p, v, __ATOMIC_RELAXED, __HIP_MEMORY_SCOPE_AGENT); }
; #define XB_SPIN(cond, bar) do { unsigned _sp = 0; while (cond) { __builtin_amdgcn_s_sleep(1); \
;     if ((++_sp & 255u) == 0u) { if (xb_ld(&(bar)[XB_TMO])) break; if (_sp > XB_SPIN_CAP) { atomicAdd(&(bar)[XB_TMO], 1u); break; } } } } while (0)
; __device__ __forceinline__ void xcd_barrier(const XcdBarrier& b, bool lead) {
;     ...
;         const unsigned old = xb_add(&bar[XB_XSUB(b.x)], 1u);
;         const unsigned gen = old / nloc;
;         if (old + 1u == (gen + 1u) * nloc) {
;             __builtin_amdgcn_fence(__ATOMIC_RELEASE, "agent");
;             asm volatile("s_waitcnt vmcnt(0)" ::: "memory");
;             const unsigned og = xb_add(&bar[XB_TOP], 1u);
;             const unsigned tg = og / nx;
;             if (og + 1u == (tg + 1u) * nx) xb_add(&bar[XB_TOPGEN], 1u);
;             else XB_SPIN(xb_ld(&bar[XB_TOPGEN]) == tg, bar);
;             __builtin_amdgcn_fence(__ATOMIC_ACQUIRE, "agent");
;             xb_add(&bar[XB_XGEN(b.x)], 1u);
;             asm volatile("s_waitcnt vmcnt(0)" ::: "memory");
;         } else {
;             XB_SPIN(xb_ld(&bar[XB_XGEN(b.x)]) == gen, bar);
.LBB0_1736:
	s_or_b64 exec, exec, s[14:15]
	v_cvt_f32_u32_e32 v4, v2
	s_waitcnt vmcnt(0)
	v_readfirstlane_b32 s12, v3
	v_sub_u32_e32 v3, 0, v2
	v_rcp_iflag_f32_e32 v4, v4
	v_add_u32_e32 v5, s12, v1
	v_mul_f32_e32 v4, 0x4f7ffffe, v4
	v_cvt_u32_f32_e32 v4, v4
	v_mul_lo_u32 v1, v3, v4
	v_mul_hi_u32 v1, v4, v1
	v_add_u32_e32 v1, v4, v1
	v_mul_hi_u32 v1, v5, v1
	v_mul_lo_u32 v3, v1, v2
	v_sub_u32_e32 v3, v5, v3
	v_add_u32_e32 v4, 1, v1
	v_cmp_ge_u32_e32 vcc, v3, v2
	s_nop 1
	v_cndmask_b32_e32 v1, v1, v4, vcc
	v_sub_u32_e32 v4, v3, v2
	v_cndmask_b32_e32 v3, v3, v4, vcc
	v_add_u32_e32 v4, 1, v1
	v_cmp_ge_u32_e32 vcc, v3, v2
	v_add_u32_e32 v3, 1, v5
	s_nop 0
	v_cndmask_b32_e32 v1, v1, v4, vcc
	v_mul_lo_u32 v4, v2, v1
	v_add_u32_e32 v2, v4, v2
	v_cmp_ne_u32_e32 vcc, v3, v2
	s_and_saveexec_b64 s[12:13], vcc
	s_xor_b64 s[12:13], exec, s[12:13]
	s_cbranch_execz .LBB0_1750
	s_waitcnt lgkmcnt(0)
	v_mov_b32_e32 v0, 0x3100
	global_load_dword v0, v0, s[56:57] offset:1024 sc1
	s_add_u32 s16, s56, 0x3500
	s_addc_u32 s17, s57, 0
	s_waitcnt vmcnt(0)
	v_cmp_eq_u32_e32 vcc, v0, v1
	s_and_saveexec_b64 s[14:15], vcc
	s_cbranch_execz .LBB0_1749
	s_mov_b32 s30, 1
	s_mov_b64 s[18:19], 0
	v_mov_b32_e32 v0, 0
	s_branch .LBB0_1740

; __device__ __forceinline__ unsigned xb_ld(unsigned* p)              { return __hip_atomic_load(p, __ATOMIC_RELAXED, __HIP_MEMORY_SCOPE_AGENT); }
; __device__ __forceinline__ unsigned xb_add(unsigned* p, unsigned v) { return __hip_atomic_fetch_add(p, v, __ATOMIC_RELAXED, __HIP_MEMORY_SCOPE_AGENT); }
; #define XB_SPIN(cond, bar) do { unsigned _sp = 0; while (cond) { __builtin_amdgcn_s_sleep(1); \
;     if ((++_sp & 255u) == 0u) { if (xb_ld(&(bar)[XB_TMO])) break; if (_sp > XB_SPIN_CAP) { atomicAdd(&(bar)[XB_TMO], 1u); break; } } } } while (0)
; __device__ __forceinline__ void xcd_barrier(const XcdBarrier& b, bool lead) {
;     ...
;         const unsigned old = xb_add(&bar[XB_XSUB(b.x)], 1u);
;         const unsigned gen = old / nloc;
;         if (old + 1u == (gen + 1u) * nloc) {
;             __builtin_amdgcn_fence(__ATOMIC_RELEASE, "agent");
;             asm volatile("s_waitcnt vmcnt(0)" ::: "memory");
;             const unsigned og = xb_add(&bar[XB_TOP], 1u);
;             const unsigned tg = og / nx;
;             if (og + 1u == (tg + 1u) * nx) xb_add(&bar[XB_TOPGEN], 1u);
;             else XB_SPIN(xb_ld(&bar[XB_TOPGEN]) == tg, bar);
;             __builtin_amdgcn_fence(__ATOMIC_ACQUIRE, "agent");
;             xb_add(&bar[XB_XGEN(b.x)], 1u);
;             asm volatile("s_waitcnt vmcnt(0)" ::: "memory");
;         } else {
;             XB_SPIN(xb_ld(&bar[XB_XGEN(b.x)]) == gen, bar);
.LBB0_1809:
	s_or_b64 exec, exec, s[14:15]
	v_cvt_f32_u32_e32 v4, v2
	s_waitcnt vmcnt(0)
	v_readfirstlane_b32 s12, v3
	v_sub_u32_e32 v3, 0, v2
	v_rcp_iflag_f32_e32 v4, v4
	v_add_u32_e32 v5, s12, v1
	v_mul_f32_e32 v4, 0x4f7ffffe, v4
	v_cvt_u32_f32_e32 v4, v4
	v_mul_lo_u32 v1, v3, v4
	v_mul_hi_u32 v1, v4, v1
	v_add_u32_e32 v1, v4, v1
	v_mul_hi_u32 v1, v5, v1
	v_mul_lo_u32 v3, v1, v2
	v_sub_u32_e32 v3, v5, v3
	v_add_u32_e32 v4, 1, v1
	v_cmp_ge_u32_e32 vcc, v3, v2
	s_nop 1
	v_cndmask_b32_e32 v1, v1, v4, vcc
	v_sub_u32_e32 v4, v3, v2
	v_cndmask_b32_e32 v3, v3, v4, vcc
	v_add_u32_e32 v4, 1, v1
	v_cmp_ge_u32_e32 vcc, v3, v2
	v_add_u32_e32 v3, 1, v5
	s_nop 0
	v_cndmask_b32_e32 v1, v1, v4, vcc
	v_mul_lo_u32 v4, v2, v1
	v_add_u32_e32 v2, v4, v2
	v_cmp_ne_u32_e32 vcc, v3, v2
	s_and_saveexec_b64 s[12:13], vcc
	s_xor_b64 s[12:13], exec, s[12:13]
	s_cbranch_execz .LBB0_1823
	s_waitcnt lgkmcnt(0)
	v_mov_b32_e32 v0, 0x3100
	global_load_dword v0, v0, s[56:57] offset:1024 sc1
	s_add_u32 s16, s56, 0x3500
	s_addc_u32 s17, s57, 0
	s_waitcnt vmcnt(0)
	v_cmp_eq_u32_e32 vcc, v0, v1
	s_and_saveexec_b64 s[14:15], vcc
	s_cbranch_execz .LBB0_1822
	s_mov_b32 s28, 1
	s_mov_b64 s[18:19], 0
	v_mov_b32_e32 v0, 0
	s_branch .LBB0_1813

; __device__ __forceinline__ unsigned xb_ld(unsigned* p)              { return __hip_atomic_load(p, __ATOMIC_RELAXED, __HIP_MEMORY_SCOPE_AGENT); }
; __device__ __forceinline__ unsigned xb_add(unsigned* p, unsigned v) { return __hip_atomic_fetch_add(p, v, __ATOMIC_RELAXED, __HIP_MEMORY_SCOPE_AGENT); }
; #define XB_SPIN(cond, bar) do { unsigned _sp = 0; while (cond) { __builtin_amdgcn_s_sleep(1); \
;     if ((++_sp & 255u) == 0u) { if (xb_ld(&(bar)[XB_TMO])) break; if (_sp > XB_SPIN_CAP) { atomicAdd(&(bar)[XB_TMO], 1u); break; } } } } while (0)
; __device__ __forceinline__ void xcd_barrier(const XcdBarrier& b, bool lead) {
;     ...
;         const unsigned old = xb_add(&bar[XB_XSUB(b.x)], 1u);
;         const unsigned gen = old / nloc;
;         if (old + 1u == (gen + 1u) * nloc) {
;             __builtin_amdgcn_fence(__ATOMIC_RELEASE, "agent");
;             asm volatile("s_waitcnt vmcnt(0)" ::: "memory");
;             const unsigned og = xb_add(&bar[XB_TOP], 1u);
;             const unsigned tg = og / nx;
;             if (og + 1u == (tg + 1u) * nx) xb_add(&bar[XB_TOPGEN], 1u);
;             else XB_SPIN(xb_ld(&bar[XB_TOPGEN]) == tg, bar);
;             __builtin_amdgcn_fence(__ATOMIC_ACQUIRE, "agent");
;             xb_add(&bar[XB_XGEN(b.x)], 1u);
;             asm volatile("s_waitcnt vmcnt(0)" ::: "memory");
;         } else {
;             XB_SPIN(xb_ld(&bar[XB_XGEN(b.x)]) == gen, bar);
.LBB0_1963:
	s_or_b64 exec, exec, s[10:11]
	v_cvt_f32_u32_e32 v4, v2
	s_waitcnt vmcnt(0)
	v_readfirstlane_b32 s3, v3
	v_sub_u32_e32 v3, 0, v2
	v_rcp_iflag_f32_e32 v4, v4
	v_add_u32_e32 v5, s3, v1
	v_mul_f32_e32 v4, 0x4f7ffffe, v4
	v_cvt_u32_f32_e32 v4, v4
	v_mul_lo_u32 v1, v3, v4
	v_mul_hi_u32 v1, v4, v1
	v_add_u32_e32 v1, v4, v1
	v_mul_hi_u32 v1, v5, v1
	v_mul_lo_u32 v3, v1, v2
	v_sub_u32_e32 v3, v5, v3
	v_add_u32_e32 v4, 1, v1
	v_cmp_ge_u32_e32 vcc, v3, v2
	s_nop 1
	v_cndmask_b32_e32 v1, v1, v4, vcc
	v_sub_u32_e32 v4, v3, v2
	v_cndmask_b32_e32 v3, v3, v4, vcc
	v_add_u32_e32 v4, 1, v1
	v_cmp_ge_u32_e32 vcc, v3, v2
	v_add_u32_e32 v3, 1, v5
	s_nop 0
	v_cndmask_b32_e32 v1, v1, v4, vcc
	v_mul_lo_u32 v4, v2, v1
	v_add_u32_e32 v2, v4, v2
	v_cmp_ne_u32_e32 vcc, v3, v2
	s_and_saveexec_b64 s[8:9], vcc
	s_xor_b64 s[8:9], exec, s[8:9]
	s_cbranch_execz .LBB0_1977
	s_waitcnt lgkmcnt(0)
	v_mov_b32_e32 v0, 0x3100
	global_load_dword v0, v0, s[56:57] offset:1024 sc1
	s_add_u32 s12, s56, 0x3500
	s_addc_u32 s13, s57, 0
	s_waitcnt vmcnt(0)
	v_cmp_eq_u32_e32 vcc, v0, v1
	s_and_saveexec_b64 s[10:11], vcc
	s_cbranch_execz .LBB0_1976
	s_mov_b32 s3, 1
	s_mov_b64 s[14:15], 0
	v_mov_b32_e32 v0, 0
	s_branch .LBB0_1967

; __device__ __forceinline__ unsigned xb_ld(unsigned* p)              { return __hip_atomic_load(p, __ATOMIC_RELAXED, __HIP_MEMORY_SCOPE_AGENT); }
; __device__ __forceinline__ unsigned xb_add(unsigned* p, unsigned v) { return __hip_atomic_fetch_add(p, v, __ATOMIC_RELAXED, __HIP_MEMORY_SCOPE_AGENT); }
; #define XB_SPIN(cond, bar) do { unsigned _sp = 0; while (cond) { __builtin_amdgcn_s_sleep(1); \
;     if ((++_sp & 255u) == 0u) { if (xb_ld(&(bar)[XB_TMO])) break; if (_sp > XB_SPIN_CAP) { atomicAdd(&(bar)[XB_TMO], 1u); break; } } } } while (0)
; __device__ __forceinline__ void xcd_barrier(const XcdBarrier& b, bool lead) {
;     ...
;         const unsigned old = xb_add(&bar[XB_XSUB(b.x)], 1u);
;         const unsigned gen = old / nloc;
;         if (old + 1u == (gen + 1u) * nloc) {
;             __builtin_amdgcn_fence(__ATOMIC_RELEASE, "agent");
;             asm volatile("s_waitcnt vmcnt(0)" ::: "memory");
;             const unsigned og = xb_add(&bar[XB_TOP], 1u);
;             const unsigned tg = og / nx;
;             if (og + 1u == (tg + 1u) * nx) xb_add(&bar[XB_TOPGEN], 1u);
;             else XB_SPIN(xb_ld(&bar[XB_TOPGEN]) == tg, bar);
;             __builtin_amdgcn_fence(__ATOMIC_ACQUIRE, "agent");
;             xb_add(&bar[XB_XGEN(b.x)], 1u);
;             asm volatile("s_waitcnt vmcnt(0)" ::: "memory");
;         } else {
;             XB_SPIN(xb_ld(&bar[XB_XGEN(b.x)]) == gen, bar);
.LBB0_2040:
	s_or_b64 exec, exec, s[44:45]
	v_cvt_f32_u32_e32 v4, v2
	s_waitcnt vmcnt(0)
	v_readfirstlane_b32 s42, v3
	v_sub_u32_e32 v3, 0, v2
	v_rcp_iflag_f32_e32 v4, v4
	v_add_u32_e32 v5, s42, v1
	v_mul_f32_e32 v4, 0x4f7ffffe, v4
	v_cvt_u32_f32_e32 v4, v4
	v_mul_lo_u32 v1, v3, v4
	v_mul_hi_u32 v1, v4, v1
	v_add_u32_e32 v1, v4, v1
	v_mul_hi_u32 v1, v5, v1
	v_mul_lo_u32 v3, v1, v2
	v_sub_u32_e32 v3, v5, v3
	v_add_u32_e32 v4, 1, v1
	v_cmp_ge_u32_e32 vcc, v3, v2
	s_nop 1
	v_cndmask_b32_e32 v1, v1, v4, vcc
	v_sub_u32_e32 v4, v3, v2
	v_cndmask_b32_e32 v3, v3, v4, vcc
	v_add_u32_e32 v4, 1, v1
	v_cmp_ge_u32_e32 vcc, v3, v2
	v_add_u32_e32 v3, 1, v5
	s_nop 0
	v_cndmask_b32_e32 v1, v1, v4, vcc
	v_mul_lo_u32 v4, v2, v1
	v_add_u32_e32 v2, v4, v2
	v_cmp_ne_u32_e32 vcc, v3, v2
	s_and_saveexec_b64 s[42:43], vcc
	s_xor_b64 s[42:43], exec, s[42:43]
	s_cbranch_execz .LBB0_2054
	s_waitcnt lgkmcnt(0)
	v_mov_b32_e32 v0, 0x3100
	global_load_dword v0, v0, s[56:57] offset:1024 sc1
	s_add_u32 s46, s56, 0x3500
	s_addc_u32 s47, s57, 0
	s_waitcnt vmcnt(0)
	v_cmp_eq_u32_e32 vcc, v0, v1
	s_and_saveexec_b64 s[44:45], vcc
	s_cbranch_execz .LBB0_2053
	s_mov_b32 s61, 1
	s_mov_b64 s[48:49], 0
	v_mov_b32_e32 v0, 0
	s_branch .LBB0_2044

; __device__ __forceinline__ unsigned xb_ld(unsigned* p)              { return __hip_atomic_load(p, __ATOMIC_RELAXED, __HIP_MEMORY_SCOPE_AGENT); }
; __device__ __forceinline__ unsigned xb_add(unsigned* p, unsigned v) { return __hip_atomic_fetch_add(p, v, __ATOMIC_RELAXED, __HIP_MEMORY_SCOPE_AGENT); }
; #define XB_SPIN(cond, bar) do { unsigned _sp = 0; while (cond) { __builtin_amdgcn_s_sleep(1); \
;     if ((++_sp & 255u) == 0u) { if (xb_ld(&(bar)[XB_TMO])) break; if (_sp > XB_SPIN_CAP) { atomicAdd(&(bar)[XB_TMO], 1u); break; } } } } while (0)
; __device__ __forceinline__ void xcd_barrier(const XcdBarrier& b, bool lead) {
;     ...
;         const unsigned old = xb_add(&bar[XB_XSUB(b.x)], 1u);
;         const unsigned gen = old / nloc;
;         if (old + 1u == (gen + 1u) * nloc) {
;             __builtin_amdgcn_fence(__ATOMIC_RELEASE, "agent");
;             asm volatile("s_waitcnt vmcnt(0)" ::: "memory");
;             const unsigned og = xb_add(&bar[XB_TOP], 1u);
;             const unsigned tg = og / nx;
;             if (og + 1u == (tg + 1u) * nx) xb_add(&bar[XB_TOPGEN], 1u);
;             else XB_SPIN(xb_ld(&bar[XB_TOPGEN]) == tg, bar);
;             __builtin_amdgcn_fence(__ATOMIC_ACQUIRE, "agent");
;             xb_add(&bar[XB_XGEN(b.x)], 1u);
;             asm volatile("s_waitcnt vmcnt(0)" ::: "memory");
;         } else {
;             XB_SPIN(xb_ld(&bar[XB_XGEN(b.x)]) == gen, bar);
.LBB0_2101:
	s_or_b64 exec, exec, s[44:45]
	v_cvt_f32_u32_e32 v4, v2
	s_waitcnt vmcnt(0)
	v_readfirstlane_b32 s42, v3
	v_sub_u32_e32 v3, 0, v2
	v_rcp_iflag_f32_e32 v4, v4
	v_add_u32_e32 v5, s42, v1
	v_mul_f32_e32 v4, 0x4f7ffffe, v4
	v_cvt_u32_f32_e32 v4, v4
	v_mul_lo_u32 v1, v3, v4
	v_mul_hi_u32 v1, v4, v1
	v_add_u32_e32 v1, v4, v1
	v_mul_hi_u32 v1, v5, v1
	v_mul_lo_u32 v3, v1, v2
	v_sub_u32_e32 v3, v5, v3
	v_add_u32_e32 v4, 1, v1
	v_cmp_ge_u32_e32 vcc, v3, v2
	s_nop 1
	v_cndmask_b32_e32 v1, v1, v4, vcc
	v_sub_u32_e32 v4, v3, v2
	v_cndmask_b32_e32 v3, v3, v4, vcc
	v_add_u32_e32 v4, 1, v1
	v_cmp_ge_u32_e32 vcc, v3, v2
	v_add_u32_e32 v3, 1, v5
	s_nop 0
	v_cndmask_b32_e32 v1, v1, v4, vcc
	v_mul_lo_u32 v4, v2, v1
	v_add_u32_e32 v2, v4, v2
	v_cmp_ne_u32_e32 vcc, v3, v2
	s_and_saveexec_b64 s[42:43], vcc
	s_xor_b64 s[42:43], exec, s[42:43]
	s_cbranch_execz .LBB0_2115
	s_waitcnt lgkmcnt(0)
	v_mov_b32_e32 v0, 0x3100
	global_load_dword v0, v0, s[56:57] offset:1024 sc1
	s_add_u32 s46, s56, 0x3500
	s_addc_u32 s47, s57, 0
	s_waitcnt vmcnt(0)
	v_cmp_eq_u32_e32 vcc, v0, v1
	s_and_saveexec_b64 s[44:45], vcc
	s_cbranch_execz .LBB0_2114
	s_mov_b32 s55, 1
	s_mov_b64 s[48:49], 0
	v_mov_b32_e32 v0, 0
	s_branch .LBB0_2105

; __device__ __forceinline__ unsigned xb_ld(unsigned* p)              { return __hip_atomic_load(p, __ATOMIC_RELAXED, __HIP_MEMORY_SCOPE_AGENT); }
; __device__ __forceinline__ unsigned xb_add(unsigned* p, unsigned v) { return __hip_atomic_fetch_add(p, v, __ATOMIC_RELAXED, __HIP_MEMORY_SCOPE_AGENT); }
; #define XB_SPIN(cond, bar) do { unsigned _sp = 0; while (cond) { __builtin_amdgcn_s_sleep(1); \
;     if ((++_sp & 255u) == 0u) { if (xb_ld(&(bar)[XB_TMO])) break; if (_sp > XB_SPIN_CAP) { atomicAdd(&(bar)[XB_TMO], 1u); break; } } } } while (0)
; __device__ __forceinline__ void xcd_barrier(const XcdBarrier& b, bool lead) {
;     ...
;         const unsigned old = xb_add(&bar[XB_XSUB(b.x)], 1u);
;         const unsigned gen = old / nloc;
;         if (old + 1u == (gen + 1u) * nloc) {
;             __builtin_amdgcn_fence(__ATOMIC_RELEASE, "agent");
;             asm volatile("s_waitcnt vmcnt(0)" ::: "memory");
;             const unsigned og = xb_add(&bar[XB_TOP], 1u);
;             const unsigned tg = og / nx;
;             if (og + 1u == (tg + 1u) * nx) xb_add(&bar[XB_TOPGEN], 1u);
;             else XB_SPIN(xb_ld(&bar[XB_TOPGEN]) == tg, bar);
;             __builtin_amdgcn_fence(__ATOMIC_ACQUIRE, "agent");
;             xb_add(&bar[XB_XGEN(b.x)], 1u);
;             asm volatile("s_waitcnt vmcnt(0)" ::: "memory");
;         } else {
;             XB_SPIN(xb_ld(&bar[XB_XGEN(b.x)]) == gen, bar);
.LBB0_2176:
	s_or_b64 exec, exec, s[8:9]
	v_cvt_f32_u32_e32 v4, v2
	s_waitcnt vmcnt(0)
	v_readfirstlane_b32 s6, v3
	v_sub_u32_e32 v3, 0, v2
	v_rcp_iflag_f32_e32 v4, v4
	v_add_u32_e32 v5, s6, v1
	v_mul_f32_e32 v4, 0x4f7ffffe, v4
	v_cvt_u32_f32_e32 v4, v4
	v_mul_lo_u32 v1, v3, v4
	v_mul_hi_u32 v1, v4, v1
	v_add_u32_e32 v1, v4, v1
	v_mul_hi_u32 v1, v5, v1
	v_mul_lo_u32 v3, v1, v2
	v_sub_u32_e32 v3, v5, v3
	v_add_u32_e32 v4, 1, v1
	v_cmp_ge_u32_e32 vcc, v3, v2
	s_nop 1
	v_cndmask_b32_e32 v1, v1, v4, vcc
	v_sub_u32_e32 v4, v3, v2
	v_cndmask_b32_e32 v3, v3, v4, vcc
	v_add_u32_e32 v4, 1, v1
	v_cmp_ge_u32_e32 vcc, v3, v2
	v_add_u32_e32 v3, 1, v5
	s_nop 0
	v_cndmask_b32_e32 v1, v1, v4, vcc
	v_mul_lo_u32 v4, v2, v1
	v_add_u32_e32 v2, v4, v2
	v_cmp_ne_u32_e32 vcc, v3, v2
	s_and_saveexec_b64 s[6:7], vcc
	s_xor_b64 s[6:7], exec, s[6:7]
	s_cbranch_execz .LBB0_2190
	s_waitcnt lgkmcnt(0)
	v_mov_b32_e32 v0, 0x3100
	global_load_dword v0, v0, s[56:57] offset:1024 sc1
	s_add_u32 s10, s56, 0x3500
	s_addc_u32 s11, s57, 0
	s_waitcnt vmcnt(0)
	v_cmp_eq_u32_e32 vcc, v0, v1
	s_and_saveexec_b64 s[8:9], vcc
	s_cbranch_execz .LBB0_2189
	s_mov_b32 s22, 1
	s_mov_b64 s[12:13], 0
	v_mov_b32_e32 v0, 0
	s_branch .LBB0_2180
